# w_in conversion transposes (kernel start + finish phase): the four guarded row loads issued together, counted vmcnt before each LDS write
# baseline (speedup 1.0000x reference)
; #define BIDX lbid()
; #define GDIM lgdim()
; DI void transpose_tile(const float* __restrict__ src, int ld_src, int k0, int n0, bool win_map, bf16_t* __restrict__ dst, int ld_dst, float* sm) {
;     ...
;     int cgp = (tid & 15) * 4, n = n0 + cgp;
;     int ns = n;
;     if (win_map) ns = n < 5904 ? n : (n < 6016 ? -1 : n - 112);
; #pragma unroll
;     for (int i = 0; i < 4; ++i) {
;       int kk = (tid >> 4) + 16 * i;
;       float4 v = make_float4(0.f, 0.f, 0.f, 0.f);
;       if (ns >= 0) v = *(const float4*)(src + (size_t)(k0 + kk) * ld_src + ns);
;       float* d = sm + kk * 65 + cgp;
;       d[0] = v.x; d[1] = v.y; d[2] = v.z; d[3] = v.w;
;     }
;   }
;   __syncthreads();
;   {
;     int n = tid >> 2, kq = (tid & 3) * 16;
;     unsigned o[8];
; #pragma unroll
;     for (int j = 0; j < 8; ++j) o[j] = pack2(sm[(kq + 2 * j) * 65 + n], sm[(kq + 2 * j + 1) * 65 + n]);
;     uint4* dp = (uint4*)(dst + (size_t)(n0 + n) * ld_dst + k0 + kq);
;     dp[0] = make_uint4(o[0], o[1], o[2], o[3]);
;     dp[1] = make_uint4(o[4], o[5], o[6], o[7]);
; DI void conv_w1(CP p, const Ptrs& w, int l, float* sm) {
;     ...
;   for (int it = BIDX; it < 126 * 32; it += GDIM) {
;     int nt = it >> 5, kt = it & 31;
;     transpose_tile(src, 7952, kt * 64, nt * 64, true, w.W1, 2048, sm);
.LBB0_46:
	v_lshlrev_b32_e32 v0, 4, v8
	v_and_b32_e32 v18, 48, v0
	v_and_b32_e32 v0, -4, v8
	v_mul_u32_u24_e32 v1, 0x41, v18
	v_lshl_add_u32 v12, v1, 2, v0
	v_ashrrev_i32_e32 v16, 2, v8
	v_add_u32_e32 v2, 0x400, v12
	s_waitcnt lgkmcnt(0)
	s_barrier
	ds_read2_b32 v[4:5], v12 offset1:65
	ds_read2_b32 v[0:1], v12 offset0:130 offset1:195
	ds_read2_b32 v[6:7], v2 offset0:4 offset1:69
	ds_read2_b32 v[2:3], v2 offset0:134 offset1:199
	v_add_u32_e32 v10, 0x800, v12
	v_add_u32_e32 v14, 0xc00, v12
	v_add_u32_e32 v16, s14, v16
	ds_read2_b32 v[8:9], v10 offset0:8 offset1:73
	ds_read2_b32 v[10:11], v10 offset0:138 offset1:203
	ds_read2_b32 v[12:13], v14 offset0:12 offset1:77
	ds_read2_b32 v[14:15], v14 offset0:142 offset1:207
	v_ashrrev_i32_e32 v17, 31, v16
	v_lshlrev_b64 v[16:17], 12, v[16:17]
	v_lshl_add_u64 v[16:17], s[4:5], 0, v[16:17]
	s_lshl_b32 s90, s13, 1
	v_lshl_add_u64 v[16:17], v[16:17], 0, s[90:91]
	v_lshlrev_b32_e32 v156, 1, v18
	v_lshl_add_u64 v[16:17], v[16:17], 0, v[156:157]
	s_waitcnt lgkmcnt(4)
	v_cvt_pk_bf16_f32 v3, v2, v3
	v_cvt_pk_bf16_f32 v2, v6, v7
	v_cvt_pk_bf16_f32 v1, v0, v1
	v_cvt_pk_bf16_f32 v0, v4, v5
	global_store_dwordx4 v[16:17], v[0:3], off
	v_readlane_b32 s6, v253, 6
	v_readlane_b32 s7, v253, 7
	s_waitcnt lgkmcnt(0)
	v_cvt_pk_bf16_f32 v3, v14, v15
	v_cvt_pk_bf16_f32 v2, v12, v13
	v_cvt_pk_bf16_f32 v1, v10, v11
	v_cvt_pk_bf16_f32 v0, v8, v9
	global_store_dwordx4 v[16:17], v[0:3], off offset:16
	s_load_dword s6, s[6:7], 0x0
	s_waitcnt lgkmcnt(0)
	s_add_i32 s12, s6, s12
	s_cmpk_gt_i32 s12, 0xfbf
	s_cbranch_scc1 .LBB0_55
.LBB0_47:
	s_lshl_b32 s6, s12, 6
	s_waitcnt vmcnt(5)
	v_mov_b32_e32 v8, v214
	s_and_b32 s13, s6, 0x7c0
	s_lshl_b32 s6, s12, 1
	s_and_b32 s14, s6, 0xffffffc0
	v_lshlrev_b32_e32 v0, 2, v8
	v_and_b32_e32 v1, 60, v0
	v_or_b32_e32 v0, s14, v1
	s_cmpk_gt_u32 s6, 0x177f
	v_add_u32_e32 v2, 0xffffff90, v0
	s_cselect_b64 vcc, -1, 0
	s_movk_i32 s6, 0x1710
	s_barrier
	v_cndmask_b32_e32 v2, -1, v2, vcc
	v_cmp_gt_i32_e32 vcc, s6, v0
	s_load_dwordx2 s[6:7], s[2:3], 0x38
	v_ashrrev_i32_e32 v9, 4, v8
	v_cndmask_b32_e32 v156, v2, v0, vcc
	v_cmp_lt_i32_e32 vcc, -1, v156
	v_mov_b32_e32 v0, 0
	s_waitcnt lgkmcnt(0)
	v_lshl_add_u64 v[6:7], v[156:157], 2, s[6:7]
	v_mov_b32_e32 v2, 0
	v_mov_b32_e32 v3, 0
	v_mov_b32_e32 v4, 0
	v_mov_b32_e32 v5, 0
	v_mov_b32_e32 v96, 0
	v_mov_b32_e32 v97, 0
	v_mov_b32_e32 v98, 0
	v_mov_b32_e32 v99, 0
	v_mov_b32_e32 v100, 0
	v_mov_b32_e32 v101, 0
	v_mov_b32_e32 v102, 0
	v_mov_b32_e32 v103, 0
	v_mov_b32_e32 v104, 0
	v_mov_b32_e32 v105, 0
	v_mov_b32_e32 v106, 0
	v_mov_b32_e32 v107, 0
	v_mov_b32_e32 v108, 0
	v_mov_b32_e32 v109, 0
	v_mov_b32_e32 v110, 0
	v_mov_b32_e32 v111, 0
	s_and_saveexec_b64 s[6:7], vcc
	s_movk_i32 s15, 0x7c40
	v_add_u32_e32 v112, s13, v9
	v_mad_i64_i32 v[112:113], s[16:17], v112, s15, v[6:7]
	global_load_dwordx4 v[96:99], v[112:113], off
	v_add3_u32 v114, v9, s13, 16
	v_mad_i64_i32 v[114:115], s[16:17], v114, s15, v[6:7]
	global_load_dwordx4 v[100:103], v[114:115], off
	v_add3_u32 v116, v9, s13, 32
	v_mad_i64_i32 v[116:117], s[16:17], v116, s15, v[6:7]
	global_load_dwordx4 v[104:107], v[116:117], off
	v_add3_u32 v118, v9, s13, 48
	v_mad_i64_i32 v[118:119], s[16:17], v118, s15, v[6:7]
	global_load_dwordx4 v[108:111], v[118:119], off
	s_or_b64 exec, exec, s[6:7]
	v_lshlrev_b32_e32 v1, 2, v1
	v_mul_lo_u32 v10, v9, s46
	v_add_u32_e32 v10, v1, v10
	s_waitcnt vmcnt(3)
	ds_write2_b32 v10, v96, v97 offset1:1
	ds_write2_b32 v10, v98, v99 offset0:2 offset1:3
	v_add_u32_e32 v4, 0x1040, v10
	v_add_u32_e32 v0, 0x1048, v10
	s_waitcnt vmcnt(2)
	ds_write2_b32 v4, v100, v101 offset1:1
	ds_write2_b32 v0, v102, v103 offset1:1
	v_add_u32_e32 v4, 0x2080, v10
	v_add_u32_e32 v0, 0x2088, v10
	s_waitcnt vmcnt(1)
	ds_write2_b32 v4, v104, v105 offset1:1
	ds_write2_b32 v0, v106, v107 offset1:1
	v_add_u32_e32 v4, 0x30c0, v10
	v_add_u32_e32 v0, 0x30c8, v10
	s_waitcnt vmcnt(0)
	ds_write2_b32 v4, v108, v109 offset1:1
	ds_write2_b32 v0, v110, v111 offset1:1
	s_branch .LBB0_46

; #define BIDX lbid()
; #define GDIM lgdim()
; DI void transpose_tile(const float* __restrict__ src, int ld_src, int k0, int n0, bool win_map, bf16_t* __restrict__ dst, int ld_dst, float* sm) {
;     ...
;     int cgp = (tid & 15) * 4, n = n0 + cgp;
;     int ns = n;
;     if (win_map) ns = n < 5904 ? n : (n < 6016 ? -1 : n - 112);
; #pragma unroll
;     for (int i = 0; i < 4; ++i) {
;       int kk = (tid >> 4) + 16 * i;
;       float4 v = make_float4(0.f, 0.f, 0.f, 0.f);
;       if (ns >= 0) v = *(const float4*)(src + (size_t)(k0 + kk) * ld_src + ns);
;       float* d = sm + kk * 65 + cgp;
;       d[0] = v.x; d[1] = v.y; d[2] = v.z; d[3] = v.w;
;     }
;   }
;   __syncthreads();
;   {
;     int n = tid >> 2, kq = (tid & 3) * 16;
;     unsigned o[8];
; #pragma unroll
;     for (int j = 0; j < 8; ++j) o[j] = pack2(sm[(kq + 2 * j) * 65 + n], sm[(kq + 2 * j + 1) * 65 + n]);
;     uint4* dp = (uint4*)(dst + (size_t)(n0 + n) * ld_dst + k0 + kq);
;     dp[0] = make_uint4(o[0], o[1], o[2], o[3]);
;     dp[1] = make_uint4(o[4], o[5], o[6], o[7]);
; DI void conv_w1(CP p, const Ptrs& w, int l, float* sm) {
;     ...
;   for (int it = BIDX; it < 126 * 32; it += GDIM) {
;     int nt = it >> 5, kt = it & 31;
;     transpose_tile(src, 7952, kt * 64, nt * 64, true, w.W1, 2048, sm);
.LBB0_783:
	v_lshlrev_b32_e32 v0, 4, v8
	v_and_b32_e32 v18, 48, v0
	v_and_b32_e32 v0, -4, v8
	v_mul_u32_u24_e32 v1, 0x41, v18
	v_lshl_add_u32 v12, v1, 2, v0
	v_ashrrev_i32_e32 v16, 2, v8
	v_add_u32_e32 v2, 0x400, v12
	s_waitcnt lgkmcnt(0)
	s_barrier
	ds_read2_b32 v[4:5], v12 offset1:65
	ds_read2_b32 v[0:1], v12 offset0:130 offset1:195
	ds_read2_b32 v[6:7], v2 offset0:4 offset1:69
	ds_read2_b32 v[2:3], v2 offset0:134 offset1:199
	v_add_u32_e32 v10, 0x800, v12
	v_add_u32_e32 v14, 0xc00, v12
	v_add_u32_e32 v16, s16, v16
	ds_read2_b32 v[8:9], v10 offset0:8 offset1:73
	ds_read2_b32 v[10:11], v10 offset0:138 offset1:203
	ds_read2_b32 v[12:13], v14 offset0:12 offset1:77
	ds_read2_b32 v[14:15], v14 offset0:142 offset1:207
	v_ashrrev_i32_e32 v17, 31, v16
	v_lshlrev_b64 v[16:17], 12, v[16:17]
	v_lshl_add_u64 v[16:17], s[6:7], 0, v[16:17]
	s_lshl_b32 s90, s15, 1
	v_lshl_add_u64 v[16:17], v[16:17], 0, s[90:91]
	v_lshlrev_b32_e32 v156, 1, v18
	v_lshl_add_u64 v[16:17], v[16:17], 0, v[156:157]
	s_waitcnt lgkmcnt(4)
	v_cvt_pk_bf16_f32 v3, v2, v3
	v_cvt_pk_bf16_f32 v2, v6, v7
	v_cvt_pk_bf16_f32 v1, v0, v1
	v_cvt_pk_bf16_f32 v0, v4, v5
	global_store_dwordx4 v[16:17], v[0:3], off
	v_readlane_b32 s12, v253, 6
	v_readlane_b32 s13, v253, 7
	s_waitcnt lgkmcnt(0)
	v_cvt_pk_bf16_f32 v3, v14, v15
	v_cvt_pk_bf16_f32 v2, v12, v13
	v_cvt_pk_bf16_f32 v1, v10, v11
	v_cvt_pk_bf16_f32 v0, v8, v9
	global_store_dwordx4 v[16:17], v[0:3], off offset:16
	s_load_dword s12, s[12:13], 0x0
	s_waitcnt lgkmcnt(0)
	s_add_i32 s14, s12, s14
	s_cmpk_lt_i32 s14, 0xfc0
	s_cbranch_scc0 .LBB0_792
.LBB0_784:
	s_lshl_b32 s12, s14, 6
	s_waitcnt vmcnt(5)
	v_mov_b32_e32 v8, v214
	s_and_b32 s15, s12, 0x7c0
	s_lshl_b32 s12, s14, 1
	s_and_b32 s16, s12, 0xffffffc0
	v_lshlrev_b32_e32 v0, 2, v8
	v_and_b32_e32 v1, 60, v0
	v_or_b32_e32 v0, s16, v1
	s_cmpk_gt_u32 s12, 0x177f
	v_add_u32_e32 v2, 0xffffff90, v0
	s_cselect_b64 vcc, -1, 0
	s_movk_i32 s12, 0x1710
	v_cndmask_b32_e32 v2, -1, v2, vcc
	v_cmp_gt_i32_e32 vcc, s12, v0
	v_ashrrev_i32_e32 v9, 4, v8
	v_mov_b32_e32 v3, 0
	v_cndmask_b32_e32 v156, v2, v0, vcc
	v_cmp_lt_i32_e32 vcc, -1, v156
	v_lshl_add_u64 v[6:7], v[156:157], 2, s[4:5]
	v_mov_b32_e32 v0, 0
	v_mov_b32_e32 v2, 0
	v_mov_b32_e32 v4, 0
	v_mov_b32_e32 v5, 0
	s_barrier
	v_mov_b32_e32 v96, 0
	v_mov_b32_e32 v97, 0
	v_mov_b32_e32 v98, 0
	v_mov_b32_e32 v99, 0
	v_mov_b32_e32 v100, 0
	v_mov_b32_e32 v101, 0
	v_mov_b32_e32 v102, 0
	v_mov_b32_e32 v103, 0
	v_mov_b32_e32 v104, 0
	v_mov_b32_e32 v105, 0
	v_mov_b32_e32 v106, 0
	v_mov_b32_e32 v107, 0
	v_mov_b32_e32 v108, 0
	v_mov_b32_e32 v109, 0
	v_mov_b32_e32 v110, 0
	v_mov_b32_e32 v111, 0
	s_and_saveexec_b64 s[12:13], vcc
	s_movk_i32 s17, 0x7c40
	v_add_u32_e32 v112, s15, v9
	v_mad_i64_i32 v[112:113], s[38:39], v112, s17, v[6:7]
	global_load_dwordx4 v[96:99], v[112:113], off
	v_add3_u32 v114, v9, s15, 16
	v_mad_i64_i32 v[114:115], s[38:39], v114, s17, v[6:7]
	global_load_dwordx4 v[100:103], v[114:115], off
	v_add3_u32 v116, v9, s15, 32
	v_mad_i64_i32 v[116:117], s[38:39], v116, s17, v[6:7]
	global_load_dwordx4 v[104:107], v[116:117], off
	v_add3_u32 v118, v9, s15, 48
	v_mad_i64_i32 v[118:119], s[38:39], v118, s17, v[6:7]
	global_load_dwordx4 v[108:111], v[118:119], off
	s_or_b64 exec, exec, s[12:13]
	s_movk_i32 s12, 0x104
	v_lshlrev_b32_e32 v1, 2, v1
	v_mul_lo_u32 v10, v9, s12
	v_add_u32_e32 v10, v1, v10
	s_waitcnt vmcnt(3)
	ds_write2_b32 v10, v96, v97 offset1:1
	ds_write2_b32 v10, v98, v99 offset0:2 offset1:3
	v_add_u32_e32 v4, 0x1040, v10
	v_add_u32_e32 v0, 0x1048, v10
	s_waitcnt vmcnt(2)
	ds_write2_b32 v4, v100, v101 offset1:1
	ds_write2_b32 v0, v102, v103 offset1:1
	v_add_u32_e32 v4, 0x2080, v10
	v_add_u32_e32 v0, 0x2088, v10
	s_waitcnt vmcnt(1)
	ds_write2_b32 v4, v104, v105 offset1:1
	ds_write2_b32 v0, v106, v107 offset1:1
	v_add_u32_e32 v4, 0x30c0, v10
	v_add_u32_e32 v0, 0x30c8, v10
	s_waitcnt vmcnt(0)
	ds_write2_b32 v4, v108, v109 offset1:1
	ds_write2_b32 v0, v110, v111 offset1:1
	s_branch .LBB0_783
